# static s_setprio 1 for waves 4-7 during mixer items
# speedup vs baseline: 1.0009x; 1.0006x over previous
; #define PHASE_PROLOG() CArgs* ka = kargs(); unsigned char* ws = ka->ws; (void)ws; const int tid = opaque_tid(), lane = tid & 63, wave = __builtin_amdgcn_readfirstlane(tid >> 6), gw = vcu * NWAVES + wave; (void)lane; (void)gw
; __global__ void __launch_bounds__(NWAVES * 64, 2) fwd_kernel(Args args_unused) {
;     ...
;         for (int item = bx; item < 128 + 128; item += G) {
;             PHASE_PROLOG();
;             const bf16* Z = (const bf16*)(ws + WS_Z); bf16* MIX = (bf16*)(ws + WS_MIX);
;             if (item < 128) retention_item(lds, Z, (bf16*)(ws + WS_YF), MIX, ka->in[6] + (size_t)layer * 2 * NH, ka->in[7] + (size_t)layer * 2048, (unsigned long long*)(ws + WS_EXP), (unsigned*)(ws + WS_CTL) + CW_FLAG + 4096 * layer, item, tid);
;             else attention_item(lds, Z, (bf16*)(ws + WS_OP), (float*)(ws + WS_LP), MIX, ka->in[8] + (size_t)layer * HD, ka->in[9] + (size_t)layer * HD, item - 128, tid);
;         }
.LBB0_330:
	s_setprio 0
	v_readlane_b32 s6, v254, 54
	s_add_i32 s53, s53, s6
	s_add_i32 s52, s52, s39
	s_add_i32 s43, s43, s6
	s_cmpk_gt_i32 s53, 0xff
	s_cbranch_scc1 .LBB0_1282
.LBB0_331:
	v_readfirstlane_b32 s6, v0
	s_nop 3
	s_lshr_b32 s6, s6, 8
	s_cmp_eq_u32 s6, 0
	s_cbranch_scc1 .Lmixprio_skip
	s_setprio 1
